# stack11 + B_MIX epilogue with row-contiguous u loads and gate stores (16-byte pieces of 64-byte row segments, turned to/from the MFMA layout through a wave-private LDS tile)
# baseline (speedup 1.0000x reference)
.LBB0_141:
	s_cmp_gt_i32 s6, 10
	s_mov_b64 s[0:1], -1
	s_cbranch_scc0 .LBB0_153
	v_readlane_b32 s0, v251, 63
	v_mov_b32_e32 v78, v150
	v_readlane_b32 s1, v250, 0
	s_andn2_b64 vcc, exec, s[0:1]
	v_readfirstlane_b32 s0, v78
	s_cbranch_vccnz .LBB0_152
	s_movk_i32 s1, 0x80
	s_ashr_i32 s0, s0, 1
	v_cmp_gt_i32_e64 s[4:5], s1, v78
	s_movk_i32 s1, 0x800
	s_andn2_b32 s0, s0, 31
	v_cmp_gt_i32_e64 s[6:7], s1, v78
	s_ashr_i32 s1, s0, 31
	s_lshl_b64 s[2:3], s[0:1], 1
	v_readlane_b32 s12, v251, 9
	v_bfe_u32 v2, v78, 5, 1
	v_readlane_b32 s13, v251, 10
	s_add_u32 s12, s12, s2
	v_lshlrev_b32_e32 v0, 3, v2
	s_addc_u32 s13, s13, s3
	v_and_b32_e32 v79, 31, v78
	v_lshlrev_b32_e32 v6, 2, v78
	v_lshl_add_u64 v[66:67], s[12:13], 0, v[0:1]
	v_readlane_b32 s12, v250, 1
	v_lshlrev_b32_e32 v80, 3, v78
	v_lshrrev_b32_e32 v4, 2, v78
	v_and_b32_e32 v5, 16, v78
	v_and_b32_e32 v6, 12, v6
	v_mul_u32_u24_e32 v7, 0x110, v79
	v_lshlrev_b32_e32 v2, 4, v2
	v_readlane_b32 s13, v250, 2
	s_add_u32 s2, s12, s2
	v_and_b32_e32 v81, 0xf8, v80
	v_ashrrev_i32_e32 v82, 5, v78
	v_and_or_b32 v4, v4, 3, v0
	s_addc_u32 s3, s13, s3
	s_movk_i32 s1, 0x240
	v_add3_u32 v94, v7, v2, 0
	v_or3_b32 v2, s0, v5, v6
	v_lshl_add_u32 v3, v81, 1, 0
	v_mul_u32_u24_e32 v4, 0x240, v4
	v_lshl_add_u64 v[68:69], s[2:3], 0, v[0:1]
	v_lshlrev_b32_e32 v83, 3, v82
	v_mul_lo_u32 v0, v82, s1
	v_lshlrev_b32_e32 v2, 1, v2
	v_readlane_b32 s0, v249, 40
	v_add_u32_e32 v84, 0x80, v83
	v_add_u32_e32 v85, 0x100, v83
	v_add_u32_e32 v86, 0x180, v83
	v_add_u32_e32 v87, 0x200, v83
	v_add_u32_e32 v88, 0x280, v83
	v_add_u32_e32 v89, 0x300, v83
	v_add_u32_e32 v90, 0x380, v83
	v_or_b32_e32 v91, 32, v79
	v_or_b32_e32 v92, 64, v79
	v_or_b32_e32 v93, 0x60, v79
	v_add3_u32 v95, v4, s0, v2
	v_add_u32_e32 v96, v3, v0
	v_and_b32_e32 v142, 63, v78
	v_lshrrev_b32_e32 v143, 2, v142
	v_and_b32_e32 v144, 3, v142
	v_lshlrev_b32_e32 v145, 4, v144
	v_readfirstlane_b32 s54, v78
	v_mov_b32_e32 v147, 0
	s_lshr_b32 s55, s54, 6
	s_lshr_b32 s58, s55, 2
	s_mul_i32 s55, s55, 0x1400
	s_lshl_b32 s58, s58, 11
	s_add_i32 s55, s55, 0x1ac00
	s_add_i32 s55, s55, s58
	v_readlane_b32 s56, v251, 9
	v_readlane_b32 s57, v251, 10
	v_lshlrev_b32_e32 v146, 13, v143
	v_add_u32_e32 v146, v146, v145
	s_add_u32 s56, s56, s54
	s_addc_u32 s57, s57, 0
	v_lshl_add_u64 v[136:137], s[56:57], 0, v[146:147]
	v_readlane_b32 s56, v250, 1
	v_readlane_b32 s57, v250, 2
	v_lshlrev_b32_e32 v146, 12, v143
	v_add_u32_e32 v146, v146, v145
	s_add_u32 s56, s56, s54
	s_addc_u32 s57, s57, 0
	v_lshl_add_u64 v[138:139], s[56:57], 0, v[146:147]
	v_mul_u32_u24_e32 v140, 0x50, v143
	v_add3_u32 v140, v140, v145, s55
	v_mul_u32_u24_e32 v141, 0x50, v79
	v_bfe_u32 v148, v78, 5, 1
	v_lshl_add_u32 v141, v148, 3, v141
	v_add_u32_e32 v141, s55, v141
	v_readlane_b32 s12, v251, 0

.LBB0_149:
	s_or_b64 exec, exec, s[0:1]
	s_lshl_b32 s0, s14, 7
	v_add_u32_e32 v22, s0, v82
	s_lshl_b32 s1, s13, 8
	v_ashrrev_i32_e32 v23, 31, v22
	v_readlane_b32 s14, v251, 9
	v_or_b32_e32 v0, s1, v81
	v_lshlrev_b64 v[2:3], 13, v[22:23]
	v_readlane_b32 s15, v251, 10
	v_lshlrev_b32_e32 v10, 2, v0
	v_lshlrev_b32_e32 v0, 1, v0
	v_lshl_add_u64 v[2:3], s[14:15], 0, v[2:3]
	v_lshl_add_u64 v[18:19], v[2:3], 0, v[0:1]
	s_movk_i32 s16, 0x1000
	v_readlane_b32 s52, v249, 13
	v_add_co_u32_e32 v18, vcc, s16, v18
	v_readlane_b32 s60, v249, 21
	v_readlane_b32 s61, v249, 22
	v_readlane_b32 s62, v249, 23
	v_readlane_b32 s63, v249, 24
	v_addc_co_u32_e32 v19, vcc, 0, v19, vcc
	s_waitcnt lgkmcnt(0)
	s_barrier
	s_waitcnt vmcnt(0)
	v_mov_b64_e32 v[6:7], v[102:103]
	v_mov_b64_e32 v[8:9], v[104:105]
	v_mov_b64_e32 v[14:15], v[106:107]
	v_mov_b64_e32 v[16:17], v[108:109]
	v_mov_b64_e32 v[2:3], v[110:111]
	v_mov_b64_e32 v[4:5], v[112:113]
	v_mov_b64_e32 v[10:11], v[114:115]
	v_mov_b64_e32 v[12:13], v[116:117]
	s_add_i32 s2, 0, 0x1a800
	v_mov_b64_e32 v[30:31], v[118:119]
	v_mov_b64_e32 v[32:33], v[120:121]
	v_add_u32_e32 v19, s2, v83
	v_add_u32_e32 v18, 16, v22
	ds_read_b64 v[38:39], v19
	v_ashrrev_i32_e32 v19, 31, v18
	v_lshlrev_b64 v[18:19], 13, v[18:19]
	v_lshl_add_u64 v[18:19], s[14:15], 0, v[18:19]
	v_lshl_add_u64 v[18:19], v[18:19], 0, v[0:1]
	v_add_co_u32_e32 v18, vcc, s16, v18
	v_add_u32_e32 v20, 32, v22
	s_nop 0
	v_addc_co_u32_e32 v19, vcc, 0, v19, vcc
	v_mov_b64_e32 v[34:35], v[122:123]
	v_mov_b64_e32 v[36:37], v[124:125]
	v_add_u32_e32 v24, 48, v22
	v_ashrrev_i32_e32 v21, 31, v20
	v_ashrrev_i32_e32 v25, 31, v24
	v_add_u32_e32 v26, 64, v22
	v_add_u32_e32 v28, 0x50, v22
	v_lshlrev_b64 v[18:19], 13, v[20:21]
	v_lshlrev_b64 v[20:21], 13, v[24:25]
	v_ashrrev_i32_e32 v27, 31, v26
	v_ashrrev_i32_e32 v29, 31, v28
	v_lshl_add_u64 v[18:19], s[14:15], 0, v[18:19]
	v_lshl_add_u64 v[20:21], s[14:15], 0, v[20:21]
	v_lshlrev_b64 v[24:25], 13, v[26:27]
	v_lshlrev_b64 v[26:27], 13, v[28:29]
	v_lshl_add_u64 v[42:43], v[18:19], 0, v[0:1]
	v_lshl_add_u64 v[28:29], v[20:21], 0, v[0:1]
	v_lshl_add_u64 v[24:25], s[14:15], 0, v[24:25]
	v_lshl_add_u64 v[40:41], s[14:15], 0, v[26:27]
	v_lshl_add_u64 v[26:27], v[24:25], 0, v[0:1]
	v_lshl_add_u64 v[24:25], v[40:41], 0, v[0:1]
	s_mov_b32 s3, 0xffff0000
	v_readlane_b32 s53, v249, 14
	v_readlane_b32 s54, v249, 15
	v_readlane_b32 s55, v249, 16
	v_readlane_b32 s56, v249, 17
	v_readlane_b32 s57, v249, 18
	v_readlane_b32 s58, v249, 19
	v_readlane_b32 s59, v249, 20
	v_readlane_b32 s64, v249, 25
	v_readlane_b32 s65, v249, 26
	v_readlane_b32 s66, v249, 27
	v_readlane_b32 s67, v249, 28
	s_waitcnt vmcnt(0)
	v_mov_b32_e32 v18, v6
	v_mov_b32_e32 v19, v8
	s_waitcnt vmcnt(4)
	v_mov_b32_e32 v20, v14
	v_mov_b32_e32 v21, v16
	v_mov_b32_e32 v8, v7
	v_mov_b32_e32 v16, v15
	s_waitcnt vmcnt(3)
	v_mov_b32_e32 v6, v2
	v_mov_b32_e32 v7, v4
	s_waitcnt vmcnt(2)
	v_mov_b32_e32 v14, v10
	v_mov_b32_e32 v15, v12
	v_mov_b32_e32 v4, v3
	v_mov_b32_e32 v12, v11
	s_waitcnt vmcnt(1)
	v_lshlrev_b32_e32 v3, 16, v31
	v_lshlrev_b32_e32 v2, 16, v30
	v_and_b32_e32 v11, 0xffff0000, v31
	v_and_b32_e32 v10, 0xffff0000, v30
	v_lshlrev_b32_e32 v31, 16, v33
	v_lshlrev_b32_e32 v30, 16, v32
	v_and_b32_e32 v33, 0xffff0000, v33
	v_and_b32_e32 v32, 0xffff0000, v32
	s_waitcnt lgkmcnt(0)
	v_pk_add_f32 v[30:31], v[30:31], v[38:39] op_sel_hi:[1,0] neg_lo:[0,1] neg_hi:[0,1]
	v_pk_add_f32 v[2:3], v[2:3], v[38:39] op_sel_hi:[1,0] neg_lo:[0,1] neg_hi:[0,1]
	v_pk_add_f32 v[10:11], v[10:11], v[38:39] op_sel_hi:[1,0] neg_lo:[0,1] neg_hi:[0,1]
	v_pk_add_f32 v[32:33], v[32:33], v[38:39] op_sel_hi:[1,0] neg_lo:[0,1] neg_hi:[0,1]
	v_pk_mul_f32 v[30:31], v[30:31], v[38:39] op_sel:[0,1]
	v_pk_mul_f32 v[2:3], v[2:3], v[38:39] op_sel:[0,1]
	v_pk_mul_f32 v[10:11], v[10:11], v[38:39] op_sel:[0,1]
	v_pk_mul_f32 v[32:33], v[32:33], v[38:39] op_sel:[0,1]
	v_pk_fma_f32 v[38:39], v[6:7], v[30:31], v[14:15]
	v_add_co_u32_e32 v30, vcc, s16, v42
	v_pk_fma_f32 v[40:41], v[4:5], v[32:33], v[12:13]
	s_nop 0
	v_addc_co_u32_e32 v31, vcc, 0, v43, vcc
	v_mov_b64_e32 v[30:31], v[200:201]
	v_mov_b64_e32 v[32:33], v[202:203]
	v_pk_fma_f32 v[2:3], v[18:19], v[2:3], v[20:21]
	v_bfe_u32 v23, v41, 16, 1
	v_bfe_u32 v44, v40, 16, 1
	v_pk_fma_f32 v[10:11], v[8:9], v[10:11], v[16:17]
	v_add3_u32 v40, v40, v44, s87
	v_add3_u32 v23, v41, v23, s87
	v_bfe_u32 v41, v2, 16, 1
	v_bfe_u32 v42, v3, 16, 1
	v_bfe_u32 v43, v38, 16, 1
	v_bfe_u32 v44, v39, 16, 1
	v_bfe_u32 v45, v11, 16, 1
	v_bfe_u32 v46, v10, 16, 1
	v_add3_u32 v39, v39, v44, s87
	v_add3_u32 v38, v38, v43, s87
	v_add3_u32 v3, v3, v42, s87
	v_add3_u32 v2, v2, v41, s87
	v_add3_u32 v10, v10, v46, s87
	v_add3_u32 v11, v11, v45, s87
	v_lshrrev_b32_e32 v2, 16, v2
	v_lshrrev_b32_e32 v3, 16, v3
	v_lshrrev_b32_e32 v38, 16, v38
	v_lshrrev_b32_e32 v39, 16, v39
	v_and_or_b32 v41, v23, s3, v39
	v_and_or_b32 v40, v40, s3, v38
	v_and_or_b32 v39, v11, s3, v3
	v_and_or_b32 v38, v10, s3, v2
	ds_write_b128 v96, v[38:41]
	v_add_u32_e32 v2, s2, v84
	ds_read_b64 v[2:3], v2
	s_waitcnt vmcnt(1)
	v_lshlrev_b32_e32 v39, 16, v35
	v_lshlrev_b32_e32 v38, 16, v34
	v_and_b32_e32 v35, 0xffff0000, v35
	v_and_b32_e32 v34, 0xffff0000, v34
	s_waitcnt lgkmcnt(0)
	v_pk_add_f32 v[34:35], v[34:35], v[2:3] op_sel_hi:[1,0] neg_lo:[0,1] neg_hi:[0,1]
	v_add_co_u32_e32 v28, vcc, s16, v28
	v_pk_mul_f32 v[34:35], v[34:35], v[2:3] op_sel:[0,1]
	v_pk_add_f32 v[38:39], v[38:39], v[2:3] op_sel_hi:[1,0] neg_lo:[0,1] neg_hi:[0,1]
	v_pk_fma_f32 v[40:41], v[8:9], v[34:35], v[16:17]
	v_lshlrev_b32_e32 v35, 16, v37
	v_lshlrev_b32_e32 v34, 16, v36
	v_pk_add_f32 v[34:35], v[34:35], v[2:3] op_sel_hi:[1,0] neg_lo:[0,1] neg_hi:[0,1]
	v_addc_co_u32_e32 v29, vcc, 0, v29, vcc
	v_pk_mul_f32 v[34:35], v[34:35], v[2:3] op_sel:[0,1]
	v_pk_mul_f32 v[38:39], v[38:39], v[2:3] op_sel:[0,1]
	v_pk_fma_f32 v[42:43], v[6:7], v[34:35], v[14:15]
	v_and_b32_e32 v35, 0xffff0000, v37
	v_and_b32_e32 v34, 0xffff0000, v36
	v_pk_add_f32 v[34:35], v[34:35], v[2:3] op_sel_hi:[1,0] neg_lo:[0,1] neg_hi:[0,1]
	v_pk_fma_f32 v[38:39], v[18:19], v[38:39], v[20:21]
	v_pk_mul_f32 v[2:3], v[34:35], v[2:3] op_sel:[0,1]
	v_mov_b64_e32 v[34:35], v[204:205]
	v_mov_b64_e32 v[36:37], v[206:207]
	v_pk_fma_f32 v[2:3], v[4:5], v[2:3], v[12:13]
	v_bfe_u32 v45, v41, 16, 1
	v_bfe_u32 v23, v3, 16, 1
	v_bfe_u32 v44, v2, 16, 1
	v_bfe_u32 v46, v40, 16, 1
	v_add3_u32 v28, v40, v46, s87
	v_add3_u32 v29, v41, v45, s87
	v_add3_u32 v2, v2, v44, s87
	v_add3_u32 v3, v3, v23, s87
	v_bfe_u32 v23, v38, 16, 1
	v_bfe_u32 v40, v39, 16, 1
	v_bfe_u32 v41, v42, 16, 1
	v_bfe_u32 v44, v43, 16, 1
	v_add3_u32 v43, v43, v44, s87
	v_add3_u32 v41, v42, v41, s87
	v_add3_u32 v39, v39, v40, s87
	v_add3_u32 v23, v38, v23, s87
	v_lshrrev_b32_e32 v23, 16, v23
	v_lshrrev_b32_e32 v38, 16, v39
	v_lshrrev_b32_e32 v39, 16, v41
	v_lshrrev_b32_e32 v40, 16, v43
	v_and_or_b32 v41, v3, s3, v40
	v_and_or_b32 v40, v2, s3, v39
	v_and_or_b32 v39, v29, s3, v38
	v_and_or_b32 v38, v28, s3, v23
	ds_write_b128 v96, v[38:41] offset:9216
	v_add_u32_e32 v2, s2, v85
	ds_read_b64 v[2:3], v2
	s_waitcnt vmcnt(1)
	v_lshlrev_b32_e32 v29, 16, v31
	v_lshlrev_b32_e32 v28, 16, v30
	v_add_co_u32_e32 v26, vcc, s16, v26
	s_waitcnt lgkmcnt(0)
	v_pk_add_f32 v[28:29], v[28:29], v[2:3] op_sel_hi:[1,0] neg_lo:[0,1] neg_hi:[0,1]
	v_addc_co_u32_e32 v27, vcc, 0, v27, vcc
	v_pk_mul_f32 v[28:29], v[28:29], v[2:3] op_sel:[0,1]
	v_add_u32_e32 v10, 0x60, v22
	v_pk_fma_f32 v[38:39], v[18:19], v[28:29], v[20:21]
	v_and_b32_e32 v29, 0xffff0000, v31
	v_and_b32_e32 v28, 0xffff0000, v30
	v_pk_add_f32 v[28:29], v[28:29], v[2:3] op_sel_hi:[1,0] neg_lo:[0,1] neg_hi:[0,1]
	v_ashrrev_i32_e32 v11, 31, v10
	v_pk_mul_f32 v[28:29], v[28:29], v[2:3] op_sel:[0,1]
	v_lshlrev_b64 v[10:11], 13, v[10:11]
	v_pk_fma_f32 v[30:31], v[8:9], v[28:29], v[16:17]
	v_lshlrev_b32_e32 v29, 16, v33
	v_lshlrev_b32_e32 v28, 16, v32
	v_pk_add_f32 v[28:29], v[28:29], v[2:3] op_sel_hi:[1,0] neg_lo:[0,1] neg_hi:[0,1]
	v_bfe_u32 v42, v30, 16, 1
	v_pk_mul_f32 v[28:29], v[28:29], v[2:3] op_sel:[0,1]
	v_add3_u32 v30, v30, v42, s87
	v_pk_fma_f32 v[40:41], v[6:7], v[28:29], v[14:15]
	v_and_b32_e32 v29, 0xffff0000, v33
	v_and_b32_e32 v28, 0xffff0000, v32
	v_pk_add_f32 v[28:29], v[28:29], v[2:3] op_sel_hi:[1,0] neg_lo:[0,1] neg_hi:[0,1]
	v_bfe_u32 v33, v31, 16, 1
	v_pk_mul_f32 v[2:3], v[28:29], v[2:3] op_sel:[0,1]
	v_add3_u32 v31, v31, v33, s87
	v_pk_fma_f32 v[2:3], v[4:5], v[2:3], v[12:13]
	v_bfe_u32 v33, v40, 16, 1
	v_bfe_u32 v23, v3, 16, 1
	v_bfe_u32 v32, v2, 16, 1
	v_add3_u32 v2, v2, v32, s87
	v_add3_u32 v3, v3, v23, s87
	v_bfe_u32 v23, v38, 16, 1
	v_bfe_u32 v32, v39, 16, 1
	v_bfe_u32 v42, v41, 16, 1
	v_add3_u32 v41, v41, v42, s87
	v_add3_u32 v33, v40, v33, s87
	v_add3_u32 v32, v39, v32, s87
	v_add3_u32 v23, v38, v23, s87
	v_mov_b64_e32 v[26:27], v[208:209]
	v_mov_b64_e32 v[28:29], v[210:211]
	v_lshrrev_b32_e32 v23, 16, v23
	v_lshrrev_b32_e32 v38, 16, v32
	v_lshrrev_b32_e32 v32, 16, v33
	v_lshrrev_b32_e32 v33, 16, v41
	v_and_or_b32 v33, v3, s3, v33
	v_and_or_b32 v32, v2, s3, v32
	v_and_or_b32 v31, v31, s3, v38
	v_and_or_b32 v30, v30, s3, v23
	ds_write_b128 v96, v[30:33] offset:18432
	v_add_u32_e32 v2, s2, v86
	ds_read_b64 v[2:3], v2
	v_add_u32_e32 v38, 0x70, v22
	s_waitcnt vmcnt(1)
	v_lshlrev_b32_e32 v23, 16, v35
	v_lshlrev_b32_e32 v22, 16, v34
	v_lshl_add_u64 v[10:11], s[14:15], 0, v[10:11]
	s_waitcnt lgkmcnt(0)
	v_pk_add_f32 v[22:23], v[22:23], v[2:3] op_sel_hi:[1,0] neg_lo:[0,1] neg_hi:[0,1]
	v_lshl_add_u64 v[10:11], v[10:11], 0, v[0:1]
	v_pk_mul_f32 v[22:23], v[22:23], v[2:3] op_sel:[0,1]
	s_nop 0
	v_pk_fma_f32 v[30:31], v[18:19], v[22:23], v[20:21]
	v_and_b32_e32 v23, 0xffff0000, v35
	v_and_b32_e32 v22, 0xffff0000, v34
	v_pk_add_f32 v[22:23], v[22:23], v[2:3] op_sel_hi:[1,0] neg_lo:[0,1] neg_hi:[0,1]
	s_nop 0
	v_pk_mul_f32 v[22:23], v[22:23], v[2:3] op_sel:[0,1]
	s_nop 0
	v_pk_fma_f32 v[32:33], v[8:9], v[22:23], v[16:17]
	v_lshlrev_b32_e32 v23, 16, v37
	v_lshlrev_b32_e32 v22, 16, v36
	v_pk_add_f32 v[22:23], v[22:23], v[2:3] op_sel_hi:[1,0] neg_lo:[0,1] neg_hi:[0,1]
	v_bfe_u32 v39, v33, 16, 1
	v_pk_mul_f32 v[22:23], v[22:23], v[2:3] op_sel:[0,1]
	v_bfe_u32 v40, v32, 16, 1
	v_pk_fma_f32 v[34:35], v[6:7], v[22:23], v[14:15]
	v_and_b32_e32 v23, 0xffff0000, v37
	v_and_b32_e32 v22, 0xffff0000, v36
	v_pk_add_f32 v[22:23], v[22:23], v[2:3] op_sel_hi:[1,0] neg_lo:[0,1] neg_hi:[0,1]
	v_add3_u32 v40, v32, v40, s87
	v_pk_mul_f32 v[2:3], v[22:23], v[2:3] op_sel:[0,1]
	v_add_co_u32_e32 v22, vcc, s16, v24
	v_pk_fma_f32 v[2:3], v[4:5], v[2:3], v[12:13]
	s_nop 0
	v_addc_co_u32_e32 v23, vcc, 0, v25, vcc
	v_mov_b64_e32 v[22:23], v[212:213]
	v_mov_b64_e32 v[24:25], v[214:215]
	v_bfe_u32 v36, v3, 16, 1
	v_bfe_u32 v37, v2, 16, 1
	v_add3_u32 v39, v33, v39, s87
	v_add3_u32 v2, v2, v37, s87
	v_add3_u32 v3, v3, v36, s87
	v_bfe_u32 v32, v30, 16, 1
	v_bfe_u32 v33, v31, 16, 1
	v_bfe_u32 v36, v34, 16, 1
	v_bfe_u32 v37, v35, 16, 1
	v_add3_u32 v35, v35, v37, s87
	v_add3_u32 v34, v34, v36, s87
	v_add3_u32 v31, v31, v33, s87
	v_add3_u32 v30, v30, v32, s87
	v_lshrrev_b32_e32 v30, 16, v30
	v_lshrrev_b32_e32 v31, 16, v31
	v_lshrrev_b32_e32 v32, 16, v34
	v_lshrrev_b32_e32 v33, 16, v35
	v_and_or_b32 v33, v3, s3, v33
	v_and_or_b32 v32, v2, s3, v32
	v_and_or_b32 v31, v39, s3, v31
	v_and_or_b32 v30, v40, s3, v30
	ds_write_b128 v96, v[30:33] offset:27648
	v_add_u32_e32 v2, s2, v87
	ds_read_b64 v[2:3], v2
	v_ashrrev_i32_e32 v39, 31, v38
	v_add_co_u32_e32 v10, vcc, s16, v10
	v_lshlrev_b64 v[34:35], 13, v[38:39]
	s_nop 0
	v_addc_co_u32_e32 v11, vcc, 0, v11, vcc
	s_waitcnt vmcnt(1)
	v_lshlrev_b32_e32 v31, 16, v27
	v_lshlrev_b32_e32 v30, 16, v26
	v_and_b32_e32 v27, 0xffff0000, v27
	v_and_b32_e32 v26, 0xffff0000, v26
	s_waitcnt lgkmcnt(0)
	v_pk_add_f32 v[26:27], v[26:27], v[2:3] op_sel_hi:[1,0] neg_lo:[0,1] neg_hi:[0,1]
	v_pk_add_f32 v[30:31], v[30:31], v[2:3] op_sel_hi:[1,0] neg_lo:[0,1] neg_hi:[0,1]
	v_pk_mul_f32 v[26:27], v[26:27], v[2:3] op_sel:[0,1]
	v_pk_mul_f32 v[30:31], v[30:31], v[2:3] op_sel:[0,1]
	v_pk_fma_f32 v[32:33], v[8:9], v[26:27], v[16:17]
	v_lshlrev_b32_e32 v27, 16, v29
	v_lshlrev_b32_e32 v26, 16, v28
	v_pk_add_f32 v[26:27], v[26:27], v[2:3] op_sel_hi:[1,0] neg_lo:[0,1] neg_hi:[0,1]
	v_pk_fma_f32 v[30:31], v[18:19], v[30:31], v[20:21]
	v_pk_mul_f32 v[26:27], v[26:27], v[2:3] op_sel:[0,1]
	v_bfe_u32 v40, v33, 16, 1
	v_pk_fma_f32 v[36:37], v[6:7], v[26:27], v[14:15]
	v_and_b32_e32 v27, 0xffff0000, v29
	v_and_b32_e32 v26, 0xffff0000, v28
	v_pk_add_f32 v[26:27], v[26:27], v[2:3] op_sel_hi:[1,0] neg_lo:[0,1] neg_hi:[0,1]
	v_bfe_u32 v41, v32, 16, 1
	v_pk_mul_f32 v[2:3], v[26:27], v[2:3] op_sel:[0,1]
	v_mov_b64_e32 v[26:27], v[216:217]
	v_mov_b64_e32 v[28:29], v[218:219]
	v_pk_fma_f32 v[2:3], v[4:5], v[2:3], v[12:13]
	v_add3_u32 v10, v32, v41, s87
	v_bfe_u32 v38, v3, 16, 1
	v_bfe_u32 v39, v2, 16, 1
	v_add3_u32 v11, v33, v40, s87
	v_add3_u32 v2, v2, v39, s87
	v_add3_u32 v3, v3, v38, s87
	v_bfe_u32 v32, v30, 16, 1
	v_bfe_u32 v33, v31, 16, 1
	v_bfe_u32 v38, v36, 16, 1
	v_bfe_u32 v39, v37, 16, 1
	v_add3_u32 v37, v37, v39, s87
	v_add3_u32 v36, v36, v38, s87
	v_add3_u32 v31, v31, v33, s87
	v_add3_u32 v30, v30, v32, s87
	v_lshrrev_b32_e32 v30, 16, v30
	v_lshrrev_b32_e32 v31, 16, v31
	v_lshrrev_b32_e32 v32, 16, v36
	v_lshrrev_b32_e32 v33, 16, v37
	v_and_or_b32 v33, v3, s3, v33
	v_and_or_b32 v32, v2, s3, v32
	v_and_or_b32 v31, v11, s3, v31
	v_and_or_b32 v30, v10, s3, v30
	ds_write_b128 v96, v[30:33] offset:36864
	v_add_u32_e32 v2, s2, v88
	ds_read_b64 v[2:3], v2
	s_waitcnt vmcnt(1)
	v_lshlrev_b32_e32 v31, 16, v23
	v_lshlrev_b32_e32 v30, 16, v22
	v_and_b32_e32 v23, 0xffff0000, v23
	v_and_b32_e32 v22, 0xffff0000, v22
	s_waitcnt lgkmcnt(0)
	v_pk_add_f32 v[22:23], v[22:23], v[2:3] op_sel_hi:[1,0] neg_lo:[0,1] neg_hi:[0,1]
	v_lshl_add_u64 v[10:11], s[14:15], 0, v[34:35]
	v_pk_mul_f32 v[22:23], v[22:23], v[2:3] op_sel:[0,1]
	v_lshl_add_u64 v[10:11], v[10:11], 0, v[0:1]
	v_pk_fma_f32 v[32:33], v[8:9], v[22:23], v[16:17]
	v_lshlrev_b32_e32 v23, 16, v25
	v_lshlrev_b32_e32 v22, 16, v24
	v_pk_add_f32 v[22:23], v[22:23], v[2:3] op_sel_hi:[1,0] neg_lo:[0,1] neg_hi:[0,1]
	v_add_co_u32_e32 v10, vcc, s16, v10
	v_pk_mul_f32 v[22:23], v[22:23], v[2:3] op_sel:[0,1]
	v_pk_add_f32 v[30:31], v[30:31], v[2:3] op_sel_hi:[1,0] neg_lo:[0,1] neg_hi:[0,1]
	v_pk_fma_f32 v[34:35], v[6:7], v[22:23], v[14:15]
	v_and_b32_e32 v23, 0xffff0000, v25
	v_and_b32_e32 v22, 0xffff0000, v24
	v_pk_add_f32 v[22:23], v[22:23], v[2:3] op_sel_hi:[1,0] neg_lo:[0,1] neg_hi:[0,1]
	v_addc_co_u32_e32 v11, vcc, 0, v11, vcc
	v_pk_mul_f32 v[30:31], v[30:31], v[2:3] op_sel:[0,1]
	v_pk_mul_f32 v[2:3], v[22:23], v[2:3] op_sel:[0,1]
	v_mov_b64_e32 v[22:23], v[220:221]
	v_mov_b64_e32 v[24:25], v[222:223]
	v_pk_fma_f32 v[2:3], v[4:5], v[2:3], v[12:13]
	v_pk_fma_f32 v[30:31], v[18:19], v[30:31], v[20:21]
	v_bfe_u32 v0, v3, 16, 1
	v_bfe_u32 v10, v2, 16, 1
	v_bfe_u32 v11, v33, 16, 1
	v_bfe_u32 v36, v32, 16, 1
	v_add3_u32 v36, v32, v36, s87
	v_add3_u32 v11, v33, v11, s87
	v_add3_u32 v2, v2, v10, s87
	v_add3_u32 v0, v3, v0, s87
	v_bfe_u32 v3, v30, 16, 1
	v_bfe_u32 v10, v31, 16, 1
	v_bfe_u32 v32, v34, 16, 1
	v_bfe_u32 v33, v35, 16, 1
	v_add3_u32 v33, v35, v33, s87
	v_add3_u32 v32, v34, v32, s87
	v_add3_u32 v10, v31, v10, s87
	v_add3_u32 v3, v30, v3, s87
	v_lshrrev_b32_e32 v3, 16, v3
	v_lshrrev_b32_e32 v10, 16, v10
	v_lshrrev_b32_e32 v30, 16, v32
	v_lshrrev_b32_e32 v31, 16, v33
	v_and_or_b32 v33, v0, s3, v31
	v_and_or_b32 v32, v2, s3, v30
	v_and_or_b32 v31, v11, s3, v10
	v_and_or_b32 v30, v36, s3, v3
	ds_write_b128 v96, v[30:33] offset:46080
	v_add_u32_e32 v0, s2, v89
	ds_read_b64 v[2:3], v0
	s_waitcnt vmcnt(1)
	v_lshlrev_b32_e32 v11, 16, v27
	v_lshlrev_b32_e32 v10, 16, v26
	v_and_b32_e32 v27, 0xffff0000, v27
	v_and_b32_e32 v26, 0xffff0000, v26
	v_lshlrev_b32_e32 v31, 16, v29
	v_lshlrev_b32_e32 v30, 16, v28
	v_and_b32_e32 v29, 0xffff0000, v29
	v_and_b32_e32 v28, 0xffff0000, v28
	s_waitcnt lgkmcnt(0)
	v_pk_add_f32 v[10:11], v[10:11], v[2:3] op_sel_hi:[1,0] neg_lo:[0,1] neg_hi:[0,1]
	v_pk_add_f32 v[26:27], v[26:27], v[2:3] op_sel_hi:[1,0] neg_lo:[0,1] neg_hi:[0,1]
	v_pk_add_f32 v[30:31], v[30:31], v[2:3] op_sel_hi:[1,0] neg_lo:[0,1] neg_hi:[0,1]
	v_pk_add_f32 v[28:29], v[28:29], v[2:3] op_sel_hi:[1,0] neg_lo:[0,1] neg_hi:[0,1]
	v_pk_mul_f32 v[10:11], v[10:11], v[2:3] op_sel:[0,1]
	v_pk_mul_f32 v[26:27], v[26:27], v[2:3] op_sel:[0,1]
	v_pk_mul_f32 v[30:31], v[30:31], v[2:3] op_sel:[0,1]
	v_pk_mul_f32 v[2:3], v[28:29], v[2:3] op_sel:[0,1]
	v_pk_fma_f32 v[26:27], v[8:9], v[26:27], v[16:17]
	v_pk_fma_f32 v[2:3], v[4:5], v[2:3], v[12:13]
	v_pk_fma_f32 v[10:11], v[18:19], v[10:11], v[20:21]
	v_pk_fma_f32 v[30:31], v[6:7], v[30:31], v[14:15]
	v_bfe_u32 v0, v3, 16, 1
	v_bfe_u32 v28, v2, 16, 1
	v_bfe_u32 v29, v27, 16, 1
	v_bfe_u32 v32, v26, 16, 1
	v_add3_u32 v26, v26, v32, s87
	v_add3_u32 v27, v27, v29, s87
	v_add3_u32 v2, v2, v28, s87
	v_add3_u32 v0, v3, v0, s87
	v_bfe_u32 v3, v10, 16, 1
	v_bfe_u32 v28, v11, 16, 1
	v_bfe_u32 v29, v30, 16, 1
	v_bfe_u32 v32, v31, 16, 1
	v_add3_u32 v31, v31, v32, s87
	v_add3_u32 v29, v30, v29, s87
	v_add3_u32 v11, v11, v28, s87
	v_add3_u32 v3, v10, v3, s87
	v_lshrrev_b32_e32 v3, 16, v3
	v_lshrrev_b32_e32 v10, 16, v11
	v_lshrrev_b32_e32 v11, 16, v29
	v_lshrrev_b32_e32 v28, 16, v31
	v_and_or_b32 v29, v0, s3, v28
	v_and_or_b32 v28, v2, s3, v11
	v_and_or_b32 v27, v27, s3, v10
	v_and_or_b32 v26, v26, s3, v3
	ds_write_b128 v96, v[26:29] offset:55296
	v_add_u32_e32 v0, s2, v90
	ds_read_b64 v[2:3], v0
	s_movk_i32 s2, 0xff00
	s_waitcnt vmcnt(0)
	v_lshlrev_b32_e32 v11, 16, v23
	v_lshlrev_b32_e32 v10, 16, v22
	s_waitcnt lgkmcnt(0)
	v_pk_add_f32 v[10:11], v[10:11], v[2:3] op_sel_hi:[1,0] neg_lo:[0,1] neg_hi:[0,1]
	s_nop 0
	v_pk_mul_f32 v[10:11], v[10:11], v[2:3] op_sel:[0,1]
	s_nop 0
	v_pk_fma_f32 v[10:11], v[18:19], v[10:11], v[20:21]
	v_and_b32_e32 v19, 0xffff0000, v23
	v_and_b32_e32 v18, 0xffff0000, v22
	v_pk_add_f32 v[18:19], v[18:19], v[2:3] op_sel_hi:[1,0] neg_lo:[0,1] neg_hi:[0,1]
	s_nop 0
	v_pk_mul_f32 v[18:19], v[18:19], v[2:3] op_sel:[0,1]
	s_nop 0
	v_pk_fma_f32 v[8:9], v[8:9], v[18:19], v[16:17]
	v_lshlrev_b32_e32 v17, 16, v25
	v_lshlrev_b32_e32 v16, 16, v24
	v_pk_add_f32 v[16:17], v[16:17], v[2:3] op_sel_hi:[1,0] neg_lo:[0,1] neg_hi:[0,1]
	s_nop 0
	v_pk_mul_f32 v[16:17], v[16:17], v[2:3] op_sel:[0,1]
	s_nop 0
	v_pk_fma_f32 v[6:7], v[6:7], v[16:17], v[14:15]
	v_and_b32_e32 v15, 0xffff0000, v25
	v_and_b32_e32 v14, 0xffff0000, v24
	v_pk_add_f32 v[14:15], v[14:15], v[2:3] op_sel_hi:[1,0] neg_lo:[0,1] neg_hi:[0,1]
	s_nop 0
	v_pk_mul_f32 v[2:3], v[14:15], v[2:3] op_sel:[0,1]
	s_nop 0
	v_pk_fma_f32 v[2:3], v[4:5], v[2:3], v[12:13]
	v_bfe_u32 v5, v9, 16, 1
	v_bfe_u32 v0, v3, 16, 1
	v_bfe_u32 v4, v2, 16, 1
	v_bfe_u32 v12, v8, 16, 1
	v_add3_u32 v8, v8, v12, s87
	v_add3_u32 v9, v9, v5, s87
	v_add3_u32 v2, v2, v4, s87
	v_add3_u32 v0, v3, v0, s87
	v_bfe_u32 v3, v10, 16, 1
	v_bfe_u32 v4, v11, 16, 1
	v_bfe_u32 v5, v6, 16, 1
	v_bfe_u32 v12, v7, 16, 1
	v_add3_u32 v7, v7, v12, s87
	v_add3_u32 v5, v6, v5, s87
	v_add3_u32 v4, v11, v4, s87
	v_add3_u32 v3, v10, v3, s87
	v_lshrrev_b32_e32 v6, 16, v3
	v_lshrrev_b32_e32 v3, 16, v4
	v_lshrrev_b32_e32 v4, 16, v5
	v_lshrrev_b32_e32 v5, 16, v7
	v_and_or_b32 v5, v0, s3, v5
	v_and_or_b32 v4, v2, s3, v4
	v_and_or_b32 v3, v9, s3, v3
	v_and_or_b32 v2, v8, s3, v6
	ds_write_b128 v96, v[2:5] offset:64512
	v_mov_b32_e32 v2, 0
	v_mov_b32_e32 v0, v95
	v_mov_b32_e32 v3, v2
	v_mov_b32_e32 v4, v2
	v_mov_b32_e32 v5, v2
	v_mov_b32_e32 v6, v2
	v_mov_b32_e32 v7, v2
	v_mov_b32_e32 v8, v2
	v_mov_b32_e32 v9, v2
	v_mov_b32_e32 v10, v2
	v_mov_b32_e32 v11, v2
	v_mov_b32_e32 v12, v2
	v_mov_b32_e32 v13, v2
	v_mov_b32_e32 v14, v2
	v_mov_b32_e32 v15, v2
	v_mov_b32_e32 v16, v2
	v_mov_b32_e32 v17, v2
	v_mov_b32_e32 v18, v2
	v_mov_b32_e32 v19, v2
	v_mov_b32_e32 v20, v2
	v_mov_b32_e32 v21, v2
	v_mov_b32_e32 v22, v2
	v_mov_b32_e32 v23, v2
	v_mov_b32_e32 v24, v2
	v_mov_b32_e32 v25, v2
	v_mov_b32_e32 v26, v2
	v_mov_b32_e32 v27, v2
	v_mov_b32_e32 v28, v2
	v_mov_b32_e32 v29, v2
	v_mov_b32_e32 v30, v2
	v_mov_b32_e32 v31, v2
	v_mov_b32_e32 v32, v2
	v_mov_b32_e32 v33, v2
	v_mov_b32_e32 v34, v2
	v_mov_b32_e32 v35, v2
	v_mov_b32_e32 v36, v2
	v_mov_b32_e32 v37, v2
	v_mov_b32_e32 v38, v2
	v_mov_b32_e32 v39, v2
	v_mov_b32_e32 v40, v2
	v_mov_b32_e32 v41, v2
	v_mov_b32_e32 v42, v2
	v_mov_b32_e32 v43, v2
	v_mov_b32_e32 v44, v2
	v_mov_b32_e32 v45, v2
	v_mov_b32_e32 v46, v2
	v_mov_b32_e32 v47, v2
	v_mov_b32_e32 v48, v2
	v_mov_b32_e32 v49, v2
	v_mov_b32_e32 v50, v2
	v_mov_b32_e32 v51, v2
	v_mov_b32_e32 v52, v2
	v_mov_b32_e32 v53, v2
	v_mov_b32_e32 v54, v2
	v_mov_b32_e32 v55, v2
	v_mov_b32_e32 v56, v2
	v_mov_b32_e32 v57, v2
	v_mov_b32_e32 v58, v2
	v_mov_b32_e32 v59, v2
	v_mov_b32_e32 v60, v2
	v_mov_b32_e32 v61, v2
	v_mov_b32_e32 v62, v2
	v_mov_b32_e32 v63, v2
	v_mov_b32_e32 v64, v2
	v_mov_b32_e32 v65, v2
	s_lshl_b32 s80, s1, 1
	v_readlane_b32 s66, v249, 27
	v_readlane_b32 s67, v249, 28
	s_lshl_b32 s54, s0, 13
	s_add_i32 s54, s54, s80
	s_mov_b32 s55, 0
	v_lshlrev_b32_e32 v198, 2, v79
	v_lshl_or_b32 v198, s13, 9, v198
	v_lshl_add_u64 v[196:197], v[136:137], 0, s[54:55]
	s_mov_b64 s[54:55], 0x20000
	global_load_dwordx4 v[160:163], v[196:197], off
	v_lshl_add_u64 v[196:197], v[196:197], 0, s[54:55]
	global_load_dwordx4 v[164:167], v[196:197], off
	v_lshl_add_u64 v[196:197], v[196:197], 0, s[54:55]
	global_load_dwordx4 v[168:171], v[196:197], off
	v_lshl_add_u64 v[196:197], v[196:197], 0, s[54:55]
	global_load_dwordx4 v[172:175], v[196:197], off
	v_lshl_add_u64 v[196:197], v[196:197], 0, s[54:55]
	global_load_dwordx4 v[176:179], v[196:197], off
	v_lshl_add_u64 v[196:197], v[196:197], 0, s[54:55]
	global_load_dwordx4 v[180:183], v[196:197], off
	v_lshl_add_u64 v[196:197], v[196:197], 0, s[54:55]
	global_load_dwordx4 v[184:187], v[196:197], off
	v_lshl_add_u64 v[196:197], v[196:197], 0, s[54:55]
	global_load_dwordx4 v[188:191], v[196:197], off
	global_load_dword v192, v198, s[66:67]
	global_load_dword v193, v198, s[66:67] offset:128
	global_load_dword v194, v198, s[66:67] offset:256
	global_load_dword v195, v198, s[66:67] offset:384
	s_waitcnt lgkmcnt(0)
	s_barrier
.LBB0_150:
	v_add_u32_e32 v74, 0xffffdc00, v0
	v_add_u32_e32 v97, s2, v94
	v_add_u32_e32 v75, 0xffffe500, v0
	ds_read_b64_tr_b16 v[70:71], v74
	ds_read_b64_tr_b16 v[72:73], v75
	s_waitcnt lgkmcnt(0)
	v_add_u32_e32 v74, 0x12100, v97
	ds_read_b128 v[74:77], v74
	s_add_i32 s2, s2, 64
	s_waitcnt lgkmcnt(0)
	v_mfma_f32_32x32x16_bf16 v[50:65], v[70:73], v[74:77], v[50:65]
	v_add_u32_e32 v74, 0x14300, v97
	ds_read_b128 v[74:77], v74
	s_cmp_eq_u32 s2, 0
	s_waitcnt lgkmcnt(0)
	v_mfma_f32_32x32x16_bf16 v[34:49], v[70:73], v[74:77], v[34:49]
	v_add_u32_e32 v74, 0x16500, v97
	ds_read_b128 v[74:77], v74
	s_waitcnt lgkmcnt(0)
	v_mfma_f32_32x32x16_bf16 v[18:33], v[70:73], v[74:77], v[18:33]
	v_add_u32_e32 v74, 0x18700, v97
	ds_read_b128 v[74:77], v74
	s_waitcnt lgkmcnt(0)
	v_mfma_f32_32x32x16_bf16 v[2:17], v[70:73], v[74:77], v[2:17]
	v_add_u32_e32 v74, 0x900, v0
	ds_read_b64_tr_b16 v[70:71], v0
	ds_read_b64_tr_b16 v[72:73], v74
	s_waitcnt lgkmcnt(0)
	v_add_u32_e32 v74, 0x12120, v97
	ds_read_b128 v[74:77], v74
	v_add_u32_e32 v0, 0x4800, v0
	s_waitcnt lgkmcnt(0)
	v_mfma_f32_32x32x16_bf16 v[50:65], v[70:73], v[74:77], v[50:65]
	v_add_u32_e32 v74, 0x14320, v97
	ds_read_b128 v[74:77], v74
	s_waitcnt lgkmcnt(0)
	v_mfma_f32_32x32x16_bf16 v[34:49], v[70:73], v[74:77], v[34:49]
	v_add_u32_e32 v74, 0x16520, v97
	ds_read_b128 v[74:77], v74
	s_waitcnt lgkmcnt(0)
	v_mfma_f32_32x32x16_bf16 v[18:33], v[70:73], v[74:77], v[18:33]
	v_add_u32_e32 v74, 0x18720, v97
	ds_read_b128 v[74:77], v74
	s_waitcnt lgkmcnt(0)
	v_mfma_f32_32x32x16_bf16 v[2:17], v[70:73], v[74:77], v[2:17]
	s_cbranch_scc0 .LBB0_150
	s_waitcnt vmcnt(0)
	s_lshl_b32 s80, s1, 1
	s_lshl_b32 s56, s0, 12
	s_add_i32 s56, s56, s80
	s_mov_b32 s57, 0
	s_mov_b64 s[58:59], 0x10000
	v_lshl_add_u64 v[72:73], v[138:139], 0, s[56:57]
	ds_write_b128 v140, v[160:163]
	ds_write_b128 v140, v[164:167] offset:1280
	ds_write_b128 v140, v[168:171] offset:2560
	ds_write_b128 v140, v[172:175] offset:3840
	s_waitcnt lgkmcnt(0)
	ds_read_b64 v[200:201], v141
	ds_read_b64 v[202:203], v141 offset:16
	ds_read_b64 v[204:205], v141 offset:32
	ds_read_b64 v[206:207], v141 offset:48
	ds_read_b64 v[208:209], v141 offset:2560
	ds_read_b64 v[210:211], v141 offset:2576
	ds_read_b64 v[212:213], v141 offset:2592
	ds_read_b64 v[214:215], v141 offset:2608
	v_add_f32_e32 v50, v50, v192
	v_add_f32_e32 v51, v51, v192
	v_add_f32_e32 v52, v52, v192
	v_add_f32_e32 v53, v53, v192
	v_add_f32_e32 v54, v54, v192
	v_add_f32_e32 v55, v55, v192
	v_add_f32_e32 v56, v56, v192
	v_add_f32_e32 v57, v57, v192
	v_add_f32_e32 v58, v58, v192
	v_add_f32_e32 v59, v59, v192
	v_add_f32_e32 v60, v60, v192
	v_add_f32_e32 v61, v61, v192
	v_add_f32_e32 v62, v62, v192
	v_add_f32_e32 v63, v63, v192
	v_add_f32_e32 v64, v64, v192
	v_add_f32_e32 v65, v65, v192
	v_add_f32_e32 v34, v34, v193
	v_add_f32_e32 v35, v35, v193
	v_add_f32_e32 v36, v36, v193
	v_add_f32_e32 v37, v37, v193
	v_add_f32_e32 v38, v38, v193
	v_add_f32_e32 v39, v39, v193
	v_add_f32_e32 v40, v40, v193
	v_add_f32_e32 v41, v41, v193
	v_add_f32_e32 v42, v42, v193
	v_add_f32_e32 v43, v43, v193
	v_add_f32_e32 v44, v44, v193
	v_add_f32_e32 v45, v45, v193
	v_add_f32_e32 v46, v46, v193
	v_add_f32_e32 v47, v47, v193
	v_add_f32_e32 v48, v48, v193
	v_add_f32_e32 v49, v49, v193
	s_waitcnt lgkmcnt(0)
	v_lshlrev_b32_e32 v216, 16, v200
	v_and_b32_e32 v217, 0xffff0000, v200
	v_lshlrev_b32_e32 v218, 16, v201
	v_and_b32_e32 v219, 0xffff0000, v201
	v_mul_f32_e32 v50, v50, v216
	v_mul_f32_e32 v51, v51, v217
	v_mul_f32_e32 v52, v52, v218
	v_mul_f32_e32 v53, v53, v219
	v_cvt_pk_bf16_f32 v200, v50, v51
	v_cvt_pk_bf16_f32 v201, v52, v53
	ds_write_b64 v141, v[200:201]
	v_lshlrev_b32_e32 v216, 16, v202
	v_and_b32_e32 v217, 0xffff0000, v202
	v_lshlrev_b32_e32 v218, 16, v203
	v_and_b32_e32 v219, 0xffff0000, v203
	v_mul_f32_e32 v54, v54, v216
	v_mul_f32_e32 v55, v55, v217
	v_mul_f32_e32 v56, v56, v218
	v_mul_f32_e32 v57, v57, v219
	v_cvt_pk_bf16_f32 v202, v54, v55
	v_cvt_pk_bf16_f32 v203, v56, v57
	ds_write_b64 v141, v[202:203] offset:16
	v_lshlrev_b32_e32 v216, 16, v204
	v_and_b32_e32 v217, 0xffff0000, v204
	v_lshlrev_b32_e32 v218, 16, v205
	v_and_b32_e32 v219, 0xffff0000, v205
	v_mul_f32_e32 v58, v58, v216
	v_mul_f32_e32 v59, v59, v217
	v_mul_f32_e32 v60, v60, v218
	v_mul_f32_e32 v61, v61, v219
	v_cvt_pk_bf16_f32 v204, v58, v59
	v_cvt_pk_bf16_f32 v205, v60, v61
	ds_write_b64 v141, v[204:205] offset:32
	v_lshlrev_b32_e32 v216, 16, v206
	v_and_b32_e32 v217, 0xffff0000, v206
	v_lshlrev_b32_e32 v218, 16, v207
	v_and_b32_e32 v219, 0xffff0000, v207
	v_mul_f32_e32 v62, v62, v216
	v_mul_f32_e32 v63, v63, v217
	v_mul_f32_e32 v64, v64, v218
	v_mul_f32_e32 v65, v65, v219
	v_cvt_pk_bf16_f32 v206, v62, v63
	v_cvt_pk_bf16_f32 v207, v64, v65
	ds_write_b64 v141, v[206:207] offset:48
	v_lshlrev_b32_e32 v216, 16, v208
	v_and_b32_e32 v217, 0xffff0000, v208
	v_lshlrev_b32_e32 v218, 16, v209
	v_and_b32_e32 v219, 0xffff0000, v209
	v_mul_f32_e32 v34, v34, v216
	v_mul_f32_e32 v35, v35, v217
	v_mul_f32_e32 v36, v36, v218
	v_mul_f32_e32 v37, v37, v219
	v_cvt_pk_bf16_f32 v208, v34, v35
	v_cvt_pk_bf16_f32 v209, v36, v37
	ds_write_b64 v141, v[208:209] offset:2560
	v_lshlrev_b32_e32 v216, 16, v210
	v_and_b32_e32 v217, 0xffff0000, v210
	v_lshlrev_b32_e32 v218, 16, v211
	v_and_b32_e32 v219, 0xffff0000, v211
	v_mul_f32_e32 v38, v38, v216
	v_mul_f32_e32 v39, v39, v217
	v_mul_f32_e32 v40, v40, v218
	v_mul_f32_e32 v41, v41, v219
	v_cvt_pk_bf16_f32 v210, v38, v39
	v_cvt_pk_bf16_f32 v211, v40, v41
	ds_write_b64 v141, v[210:211] offset:2576
	v_lshlrev_b32_e32 v216, 16, v212
	v_and_b32_e32 v217, 0xffff0000, v212
	v_lshlrev_b32_e32 v218, 16, v213
	v_and_b32_e32 v219, 0xffff0000, v213
	v_mul_f32_e32 v42, v42, v216
	v_mul_f32_e32 v43, v43, v217
	v_mul_f32_e32 v44, v44, v218
	v_mul_f32_e32 v45, v45, v219
	v_cvt_pk_bf16_f32 v212, v42, v43
	v_cvt_pk_bf16_f32 v213, v44, v45
	ds_write_b64 v141, v[212:213] offset:2592
	v_lshlrev_b32_e32 v216, 16, v214
	v_and_b32_e32 v217, 0xffff0000, v214
	v_lshlrev_b32_e32 v218, 16, v215
	v_and_b32_e32 v219, 0xffff0000, v215
	v_mul_f32_e32 v46, v46, v216
	v_mul_f32_e32 v47, v47, v217
	v_mul_f32_e32 v48, v48, v218
	v_mul_f32_e32 v49, v49, v219
	v_cvt_pk_bf16_f32 v214, v46, v47
	v_cvt_pk_bf16_f32 v215, v48, v49
	ds_write_b64 v141, v[214:215] offset:2608
	s_waitcnt lgkmcnt(0)
	ds_read_b128 v[160:163], v140
	ds_read_b128 v[164:167], v140 offset:1280
	ds_read_b128 v[168:171], v140 offset:2560
	ds_read_b128 v[172:175], v140 offset:3840
	s_waitcnt lgkmcnt(3)
	global_store_dwordx4 v[72:73], v[160:163], off
	v_lshl_add_u64 v[72:73], v[72:73], 0, s[58:59]
	s_waitcnt lgkmcnt(2)
	global_store_dwordx4 v[72:73], v[164:167], off
	v_lshl_add_u64 v[72:73], v[72:73], 0, s[58:59]
	s_waitcnt lgkmcnt(1)
	global_store_dwordx4 v[72:73], v[168:171], off
	v_lshl_add_u64 v[72:73], v[72:73], 0, s[58:59]
	s_waitcnt lgkmcnt(0)
	global_store_dwordx4 v[72:73], v[172:175], off
	v_lshl_add_u64 v[72:73], v[72:73], 0, s[58:59]
	ds_write_b128 v140, v[176:179]
	ds_write_b128 v140, v[180:183] offset:1280
	ds_write_b128 v140, v[184:187] offset:2560
	ds_write_b128 v140, v[188:191] offset:3840
	s_waitcnt lgkmcnt(0)
	ds_read_b64 v[200:201], v141
	ds_read_b64 v[202:203], v141 offset:16
	ds_read_b64 v[204:205], v141 offset:32
	ds_read_b64 v[206:207], v141 offset:48
	ds_read_b64 v[208:209], v141 offset:2560
	ds_read_b64 v[210:211], v141 offset:2576
	ds_read_b64 v[212:213], v141 offset:2592
	ds_read_b64 v[214:215], v141 offset:2608
	v_add_f32_e32 v18, v18, v194
	v_add_f32_e32 v19, v19, v194
	v_add_f32_e32 v20, v20, v194
	v_add_f32_e32 v21, v21, v194
	v_add_f32_e32 v22, v22, v194
	v_add_f32_e32 v23, v23, v194
	v_add_f32_e32 v24, v24, v194
	v_add_f32_e32 v25, v25, v194
	v_add_f32_e32 v26, v26, v194
	v_add_f32_e32 v27, v27, v194
	v_add_f32_e32 v28, v28, v194
	v_add_f32_e32 v29, v29, v194
	v_add_f32_e32 v30, v30, v194
	v_add_f32_e32 v31, v31, v194
	v_add_f32_e32 v32, v32, v194
	v_add_f32_e32 v33, v33, v194
	v_add_f32_e32 v2, v2, v195
	v_add_f32_e32 v3, v3, v195
	v_add_f32_e32 v4, v4, v195
	v_add_f32_e32 v5, v5, v195
	v_add_f32_e32 v6, v6, v195
	v_add_f32_e32 v7, v7, v195
	v_add_f32_e32 v8, v8, v195
	v_add_f32_e32 v9, v9, v195
	v_add_f32_e32 v10, v10, v195
	v_add_f32_e32 v11, v11, v195
	v_add_f32_e32 v12, v12, v195
	v_add_f32_e32 v13, v13, v195
	v_add_f32_e32 v14, v14, v195
	v_add_f32_e32 v15, v15, v195
	v_add_f32_e32 v16, v16, v195
	v_add_f32_e32 v17, v17, v195
	s_waitcnt lgkmcnt(0)
	v_lshlrev_b32_e32 v216, 16, v200
	v_and_b32_e32 v217, 0xffff0000, v200
	v_lshlrev_b32_e32 v218, 16, v201
	v_and_b32_e32 v219, 0xffff0000, v201
	v_mul_f32_e32 v18, v18, v216
	v_mul_f32_e32 v19, v19, v217
	v_mul_f32_e32 v20, v20, v218
	v_mul_f32_e32 v21, v21, v219
	v_cvt_pk_bf16_f32 v200, v18, v19
	v_cvt_pk_bf16_f32 v201, v20, v21
	ds_write_b64 v141, v[200:201]
	v_lshlrev_b32_e32 v216, 16, v202
	v_and_b32_e32 v217, 0xffff0000, v202
	v_lshlrev_b32_e32 v218, 16, v203
	v_and_b32_e32 v219, 0xffff0000, v203
	v_mul_f32_e32 v22, v22, v216
	v_mul_f32_e32 v23, v23, v217
	v_mul_f32_e32 v24, v24, v218
	v_mul_f32_e32 v25, v25, v219
	v_cvt_pk_bf16_f32 v202, v22, v23
	v_cvt_pk_bf16_f32 v203, v24, v25
	ds_write_b64 v141, v[202:203] offset:16
	v_lshlrev_b32_e32 v216, 16, v204
	v_and_b32_e32 v217, 0xffff0000, v204
	v_lshlrev_b32_e32 v218, 16, v205
	v_and_b32_e32 v219, 0xffff0000, v205
	v_mul_f32_e32 v26, v26, v216
	v_mul_f32_e32 v27, v27, v217
	v_mul_f32_e32 v28, v28, v218
	v_mul_f32_e32 v29, v29, v219
	v_cvt_pk_bf16_f32 v204, v26, v27
	v_cvt_pk_bf16_f32 v205, v28, v29
	ds_write_b64 v141, v[204:205] offset:32
	v_lshlrev_b32_e32 v216, 16, v206
	v_and_b32_e32 v217, 0xffff0000, v206
	v_lshlrev_b32_e32 v218, 16, v207
	v_and_b32_e32 v219, 0xffff0000, v207
	v_mul_f32_e32 v30, v30, v216
	v_mul_f32_e32 v31, v31, v217
	v_mul_f32_e32 v32, v32, v218
	v_mul_f32_e32 v33, v33, v219
	v_cvt_pk_bf16_f32 v206, v30, v31
	v_cvt_pk_bf16_f32 v207, v32, v33
	ds_write_b64 v141, v[206:207] offset:48
	v_lshlrev_b32_e32 v216, 16, v208
	v_and_b32_e32 v217, 0xffff0000, v208
	v_lshlrev_b32_e32 v218, 16, v209
	v_and_b32_e32 v219, 0xffff0000, v209
	v_mul_f32_e32 v2, v2, v216
	v_mul_f32_e32 v3, v3, v217
	v_mul_f32_e32 v4, v4, v218
	v_mul_f32_e32 v5, v5, v219
	v_cvt_pk_bf16_f32 v208, v2, v3
	v_cvt_pk_bf16_f32 v209, v4, v5
	ds_write_b64 v141, v[208:209] offset:2560
	v_lshlrev_b32_e32 v216, 16, v210
	v_and_b32_e32 v217, 0xffff0000, v210
	v_lshlrev_b32_e32 v218, 16, v211
	v_and_b32_e32 v219, 0xffff0000, v211
	v_mul_f32_e32 v6, v6, v216
	v_mul_f32_e32 v7, v7, v217
	v_mul_f32_e32 v8, v8, v218
	v_mul_f32_e32 v9, v9, v219
	v_cvt_pk_bf16_f32 v210, v6, v7
	v_cvt_pk_bf16_f32 v211, v8, v9
	ds_write_b64 v141, v[210:211] offset:2576
	v_lshlrev_b32_e32 v216, 16, v212
	v_and_b32_e32 v217, 0xffff0000, v212
	v_lshlrev_b32_e32 v218, 16, v213
	v_and_b32_e32 v219, 0xffff0000, v213
	v_mul_f32_e32 v10, v10, v216
	v_mul_f32_e32 v11, v11, v217
	v_mul_f32_e32 v12, v12, v218
	v_mul_f32_e32 v13, v13, v219
	v_cvt_pk_bf16_f32 v212, v10, v11
	v_cvt_pk_bf16_f32 v213, v12, v13
	ds_write_b64 v141, v[212:213] offset:2592
	v_lshlrev_b32_e32 v216, 16, v214
	v_and_b32_e32 v217, 0xffff0000, v214
	v_lshlrev_b32_e32 v218, 16, v215
	v_and_b32_e32 v219, 0xffff0000, v215
	v_mul_f32_e32 v14, v14, v216
	v_mul_f32_e32 v15, v15, v217
	v_mul_f32_e32 v16, v16, v218
	v_mul_f32_e32 v17, v17, v219
	v_cvt_pk_bf16_f32 v214, v14, v15
	v_cvt_pk_bf16_f32 v215, v16, v17
	ds_write_b64 v141, v[214:215] offset:2608
	s_waitcnt lgkmcnt(0)
	ds_read_b128 v[176:179], v140
	ds_read_b128 v[180:183], v140 offset:1280
	ds_read_b128 v[184:187], v140 offset:2560
	ds_read_b128 v[188:191], v140 offset:3840
	s_waitcnt lgkmcnt(3)
	global_store_dwordx4 v[72:73], v[176:179], off
	v_lshl_add_u64 v[72:73], v[72:73], 0, s[58:59]
	s_waitcnt lgkmcnt(2)
	global_store_dwordx4 v[72:73], v[180:183], off
	v_lshl_add_u64 v[72:73], v[72:73], 0, s[58:59]
	s_waitcnt lgkmcnt(1)
	global_store_dwordx4 v[72:73], v[184:187], off
	v_lshl_add_u64 v[72:73], v[72:73], 0, s[58:59]
	s_waitcnt lgkmcnt(0)
	global_store_dwordx4 v[72:73], v[188:191], off
	v_readlane_b32 s52, v249, 13
	v_readlane_b32 s53, v249, 14
	v_readlane_b32 s54, v249, 15
	v_readlane_b32 s55, v249, 16
	v_readlane_b32 s56, v249, 17
	v_readlane_b32 s57, v249, 18
	v_readlane_b32 s58, v249, 19
	v_readlane_b32 s59, v249, 20
	v_readlane_b32 s62, v249, 23
	v_readlane_b32 s63, v249, 24
	v_readlane_b32 s64, v249, 25
	v_readlane_b32 s65, v249, 26
	v_readlane_b32 s66, v249, 27
	v_readlane_b32 s67, v249, 28
	v_readlane_b32 s23, v249, 41
	v_readlane_b32 s60, v248, 31
	v_readlane_b32 s61, v248, 32
	s_add_i32 s12, s12, s34
	s_cmpk_gt_i32 s12, 0x3ff
	s_cbranch_scc0 .LBB0_144
